# attention tile loop rewritten: software-pipelined QK/exp/PV interleave, 4 S sets, exp in MFMA gaps; counted vmcnt at tile barrier
# speedup vs baseline: 1.0278x; 1.0278x over previous
.LBB0_34:
	v_mov_b32_e32 v12, v208
	s_xor_b64 s[84:85], s[86:87], -1
	v_readfirstlane_b32 s56, v12
	s_ashr_i32 s58, s56, 6
	s_and_b64 s[60:61], s[86:87], exec
	v_and_b32_e32 v13, 63, v12
	s_cselect_b32 s57, s33, s11
	s_lshl_b32 s27, s57, 8
	v_lshl_or_b32 v0, s58, 9, v13
	s_or_b32 s53, s27, s52
	v_ashrrev_i32_e32 v0, 4, v0
	v_xor_b32_e32 v2, v0, v12
	v_add_u32_e32 v0, s53, v0
	v_ashrrev_i32_e32 v1, 31, v0
	v_lshlrev_b64 v[0:1], 10, v[0:1]
	v_lshlrev_b32_e32 v2, 4, v2
	s_lshl_b32 s27, s58, 3
	v_lshl_add_u64 v[0:1], s[72:73], 0, v[0:1]
	v_and_b32_e32 v144, 0xf0, v2
	s_lshl_b32 s59, s58, 13
	s_add_i32 s60, 0, 0x18000
	v_lshl_add_u64 v[0:1], v[0:1], 0, v[144:145]
	s_add_i32 m0, s60, s59
	s_or_b32 s61, s27, 1
	global_load_lds_dwordx4 v[0:1], off
	v_lshl_or_b32 v0, s61, 6, v13
	v_ashrrev_i32_e32 v0, 4, v0
	v_xor_b32_e32 v2, v0, v12
	v_add_u32_e32 v0, s53, v0
	v_ashrrev_i32_e32 v1, 31, v0
	v_lshlrev_b64 v[0:1], 10, v[0:1]
	v_lshlrev_b32_e32 v2, 4, v2
	v_lshl_add_u64 v[0:1], s[72:73], 0, v[0:1]
	v_and_b32_e32 v144, 0xf0, v2
	s_lshl_b32 s61, s61, 10
	v_lshl_add_u64 v[0:1], v[0:1], 0, v[144:145]
	s_add_i32 m0, s60, s61
	s_or_b32 s61, s27, 2
	global_load_lds_dwordx4 v[0:1], off
	v_lshl_or_b32 v0, s61, 6, v13
	v_ashrrev_i32_e32 v0, 4, v0
	v_xor_b32_e32 v2, v0, v12
	v_add_u32_e32 v0, s53, v0
	v_ashrrev_i32_e32 v1, 31, v0
	v_lshlrev_b64 v[0:1], 10, v[0:1]
	v_lshlrev_b32_e32 v2, 4, v2
	v_lshl_add_u64 v[0:1], s[72:73], 0, v[0:1]
	v_and_b32_e32 v144, 0xf0, v2
	s_lshl_b32 s61, s61, 10
	v_lshl_add_u64 v[0:1], v[0:1], 0, v[144:145]
	s_add_i32 m0, s60, s61
	s_or_b32 s61, s27, 3
	global_load_lds_dwordx4 v[0:1], off
	v_lshl_or_b32 v0, s61, 6, v13
	v_ashrrev_i32_e32 v0, 4, v0
	v_xor_b32_e32 v2, v0, v12
	v_add_u32_e32 v0, s53, v0
	v_ashrrev_i32_e32 v1, 31, v0
	v_lshlrev_b64 v[0:1], 10, v[0:1]
	v_lshlrev_b32_e32 v2, 4, v2
	v_lshl_add_u64 v[0:1], s[72:73], 0, v[0:1]
	v_and_b32_e32 v144, 0xf0, v2
	s_lshl_b32 s61, s61, 10
	v_lshl_add_u64 v[0:1], v[0:1], 0, v[144:145]
	s_add_i32 m0, s60, s61
	s_or_b32 s61, s27, 4
	global_load_lds_dwordx4 v[0:1], off
	v_lshl_or_b32 v0, s61, 6, v13
	v_ashrrev_i32_e32 v0, 4, v0
	v_xor_b32_e32 v2, v0, v12
	v_add_u32_e32 v0, s53, v0
	v_ashrrev_i32_e32 v1, 31, v0
	v_lshlrev_b64 v[0:1], 10, v[0:1]
	v_lshlrev_b32_e32 v2, 4, v2
	v_lshl_add_u64 v[0:1], s[72:73], 0, v[0:1]
	v_and_b32_e32 v144, 0xf0, v2
	s_lshl_b32 s61, s61, 10
	v_lshl_add_u64 v[0:1], v[0:1], 0, v[144:145]
	s_add_i32 m0, s60, s61
	s_or_b32 s61, s27, 5
	global_load_lds_dwordx4 v[0:1], off
	v_lshl_or_b32 v0, s61, 6, v13
	v_ashrrev_i32_e32 v0, 4, v0
	v_xor_b32_e32 v2, v0, v12
	v_add_u32_e32 v0, s53, v0
	v_ashrrev_i32_e32 v1, 31, v0
	v_lshlrev_b64 v[0:1], 10, v[0:1]
	v_lshlrev_b32_e32 v2, 4, v2
	v_lshl_add_u64 v[0:1], s[72:73], 0, v[0:1]
	v_and_b32_e32 v144, 0xf0, v2
	s_lshl_b32 s61, s61, 10
	v_lshl_add_u64 v[0:1], v[0:1], 0, v[144:145]
	s_add_i32 m0, s60, s61
	s_or_b32 s61, s27, 6
	global_load_lds_dwordx4 v[0:1], off
	v_lshl_or_b32 v0, s61, 6, v13
	v_ashrrev_i32_e32 v0, 4, v0
	v_xor_b32_e32 v2, v0, v12
	v_add_u32_e32 v0, s53, v0
	v_ashrrev_i32_e32 v1, 31, v0
	v_lshlrev_b64 v[0:1], 10, v[0:1]
	v_lshlrev_b32_e32 v2, 4, v2
	v_lshl_add_u64 v[0:1], s[72:73], 0, v[0:1]
	v_and_b32_e32 v144, 0xf0, v2
	s_lshl_b32 s61, s61, 10
	v_lshl_add_u64 v[0:1], v[0:1], 0, v[144:145]
	s_add_i32 m0, s60, s61
	s_or_b32 s27, s27, 7
	global_load_lds_dwordx4 v[0:1], off
	v_lshl_or_b32 v0, s27, 6, v13
	v_ashrrev_i32_e32 v0, 4, v0
	v_xor_b32_e32 v2, v0, v12
	v_add_u32_e32 v0, s53, v0
	v_ashrrev_i32_e32 v1, 31, v0
	v_lshlrev_b64 v[0:1], 10, v[0:1]
	v_lshlrev_b32_e32 v2, 4, v2
	v_lshl_add_u64 v[0:1], s[72:73], 0, v[0:1]
	v_and_b32_e32 v144, 0xf0, v2
	s_lshl_b32 s27, s27, 10
	v_lshl_add_u64 v[0:1], v[0:1], 0, v[144:145]
	s_add_i32 m0, s60, s27
	s_lshl_b32 s27, s58, 11
	global_load_lds_dwordx4 v[0:1], off
	v_lshl_or_b32 v1, s58, 7, v13
	v_ashrrev_i32_e32 v0, 4, v1
	v_xor_b32_e32 v2, v0, v12
	v_lshlrev_b32_e32 v0, 9, v0
	v_lshlrev_b32_e32 v2, 3, v2
	v_and_or_b32 v0, v2, s3, v0
	v_bfe_u32 v2, v12, 4, 2
	v_xor_b32_e32 v2, v2, v12
	v_lshlrev_b32_e32 v2, 3, v2
	v_lshlrev_b32_e32 v3, 9, v1
	v_and_b32_e32 v14, 56, v2
	v_or_b32_e32 v1, 64, v1
	v_and_or_b32 v2, v3, s5, v14
	v_ashrrev_i32_e32 v3, 4, v1
	v_xor_b32_e32 v4, v3, v12
	v_lshlrev_b32_e32 v3, 9, v3
	v_lshlrev_b32_e32 v4, 3, v4
	v_and_or_b32 v4, v4, s3, v3
	v_lshrrev_b32_e32 v3, 4, v1
	v_xor_b32_e32 v3, v3, v12
	v_lshlrev_b32_e32 v8, 9, v1
	v_lshlrev_b32_e32 v1, 3, v3
	v_and_b32_e32 v9, 56, v1
	v_ashrrev_i32_e32 v1, 31, v0
	v_lshlrev_b64 v[0:1], 1, v[0:1]
	s_add_i32 s27, s27, 0
	v_lshl_add_u64 v[6:7], s[74:75], 0, v[0:1]
	s_mov_b32 m0, s27
	v_ashrrev_i32_e32 v3, 31, v2
	v_ashrrev_i32_e32 v5, 31, v4
	global_load_lds_dwordx4 v[6:7], off
	v_lshl_add_u64 v[2:3], v[2:3], 1, s[76:77]
	s_add_i32 m0, s27, 0x4000
	v_lshlrev_b64 v[4:5], 1, v[4:5]
	global_load_lds_dwordx4 v[2:3], off
	v_lshl_add_u64 v[6:7], s[74:75], 0, v[4:5]
	s_add_i32 m0, s27, 0x400
	s_movk_i32 s60, 0xf000
	global_load_lds_dwordx4 v[6:7], off
	v_and_or_b32 v6, v8, s60, v9
	v_ashrrev_i32_e32 v7, 31, v6
	v_lshlrev_b64 v[6:7], 1, v[6:7]
	v_lshl_add_u64 v[8:9], s[76:77], 0, v[6:7]
	s_add_i32 m0, s27, 0x4400
	v_lshl_add_u64 v[10:11], s[78:79], 0, v[0:1]
	global_load_lds_dwordx4 v[8:9], off
	s_add_i32 m0, s27, 0x8000
	v_lshl_add_u64 v[2:3], v[2:3], 0, s[18:19]
	global_load_lds_dwordx4 v[10:11], off
	s_add_i32 m0, s27, 0xc000
	v_lshl_add_u64 v[146:147], s[80:81], 0, v[0:1]
	global_load_lds_dwordx4 v[2:3], off
	v_lshl_add_u64 v[2:3], s[78:79], 0, v[4:5]
	s_add_i32 m0, s27, 0x8400
	v_lshlrev_b32_e32 v0, 9, v13
	global_load_lds_dwordx4 v[2:3], off
	v_lshl_add_u64 v[2:3], v[8:9], 0, s[18:19]
	s_add_i32 m0, s27, 0xc400
	v_lshl_or_b32 v0, s58, 16, v0
	global_load_lds_dwordx4 v[2:3], off
	v_bfe_u32 v3, v12, 5, 1
	v_and_b32_e32 v2, 31, v12
	v_bitop3_b32 v9, v3, v12, 15 bitop3:0x78
	v_lshlrev_b32_e32 v8, 8, v2
	v_lshlrev_b32_e32 v9, 4, v9
	v_or_b32_e32 v196, v9, v8
	v_or3_b32 v8, s59, v8, v9
	v_add_u32_e32 v197, 0x18000, v8
	v_lshrrev_b32_e32 v8, 1, v12
	v_bitop3_b32 v3, v3, v8, 7 bitop3:0x78
	v_and_or_b32 v0, v0, s5, v14
	s_waitcnt vmcnt(4)
	v_lshlrev_b32_e32 v2, 7, v2
	v_lshlrev_b32_e32 v3, 4, v3
	v_ashrrev_i32_e32 v1, 31, v0
	v_mov_b32_e32 v14, v145
	v_mov_b32_e32 v15, v145
	s_lshl_b32 s57, s57, 2
	s_ashr_i32 s60, s56, 7
	v_or3_b32 v198, v3, v2, s7
	v_lshl_add_u64 v[148:149], s[80:81], 0, v[4:5]
	v_lshl_add_u64 v[152:153], v[0:1], 1, s[82:83]
	v_lshl_add_u64 v[154:155], s[82:83], 0, v[6:7]
	v_mov_b32_e32 v144, v145
	v_mov_b32_e32 v0, v145
	v_mov_b32_e32 v1, v145
	v_mov_b32_e32 v2, v145
	v_mov_b32_e32 v3, v145
	v_mov_b32_e32 v4, v145
	v_mov_b32_e32 v5, v145
	v_mov_b32_e32 v6, v145
	v_mov_b32_e32 v7, v145
	v_mov_b32_e32 v8, v145
	v_mov_b32_e32 v9, v145
	v_mov_b32_e32 v10, v145
	v_mov_b32_e32 v11, v145
	v_mov_b32_e32 v12, v145
	v_mov_b32_e32 v13, v145
	v_mov_b64_e32 v[46:47], v[14:15]
	v_mov_b64_e32 v[78:79], v[14:15]
	v_mov_b64_e32 v[110:111], v[14:15]
	v_mov_b64_e32 v[30:31], v[14:15]
	v_mov_b64_e32 v[62:63], v[14:15]
	v_mov_b64_e32 v[94:95], v[14:15]
	v_mov_b64_e32 v[126:127], v[14:15]
	s_add_i32 s56, s57, 4
	s_add_i32 s57, s60, s57
	s_mov_b32 s61, 0x10000
	s_mov_b32 s60, 0
	v_mov_b64_e32 v[44:45], v[12:13]
	v_mov_b64_e32 v[42:43], v[10:11]
	v_mov_b64_e32 v[40:41], v[8:9]
	v_mov_b64_e32 v[38:39], v[6:7]
	v_mov_b64_e32 v[36:37], v[4:5]
	v_mov_b64_e32 v[34:35], v[2:3]
	v_mov_b64_e32 v[32:33], v[0:1]
	v_mov_b64_e32 v[76:77], v[12:13]
	v_mov_b64_e32 v[74:75], v[10:11]
	v_mov_b64_e32 v[72:73], v[8:9]
	v_mov_b64_e32 v[70:71], v[6:7]
	v_mov_b64_e32 v[68:69], v[4:5]
	v_mov_b64_e32 v[66:67], v[2:3]
	v_mov_b64_e32 v[64:65], v[0:1]
	v_mov_b64_e32 v[108:109], v[12:13]
	v_mov_b64_e32 v[106:107], v[10:11]
	v_mov_b64_e32 v[104:105], v[8:9]
	v_mov_b64_e32 v[102:103], v[6:7]
	v_mov_b64_e32 v[100:101], v[4:5]
	v_mov_b64_e32 v[98:99], v[2:3]
	v_mov_b64_e32 v[96:97], v[0:1]
	v_mov_b64_e32 v[28:29], v[12:13]
	v_mov_b64_e32 v[26:27], v[10:11]
	v_mov_b64_e32 v[24:25], v[8:9]
	v_mov_b64_e32 v[22:23], v[6:7]
	v_mov_b64_e32 v[20:21], v[4:5]
	v_mov_b64_e32 v[18:19], v[2:3]
	v_mov_b64_e32 v[16:17], v[0:1]
	v_mov_b64_e32 v[60:61], v[12:13]
	v_mov_b64_e32 v[58:59], v[10:11]
	v_mov_b64_e32 v[56:57], v[8:9]
	v_mov_b64_e32 v[54:55], v[6:7]
	v_mov_b64_e32 v[52:53], v[4:5]
	v_mov_b64_e32 v[50:51], v[2:3]
	v_mov_b64_e32 v[48:49], v[0:1]
	v_mov_b64_e32 v[92:93], v[12:13]
	v_mov_b64_e32 v[90:91], v[10:11]
	v_mov_b64_e32 v[88:89], v[8:9]
	v_mov_b64_e32 v[86:87], v[6:7]
	v_mov_b64_e32 v[84:85], v[4:5]
	v_mov_b64_e32 v[82:83], v[2:3]
	v_mov_b64_e32 v[80:81], v[0:1]
	v_mov_b64_e32 v[124:125], v[12:13]
	v_mov_b64_e32 v[122:123], v[10:11]
	v_mov_b64_e32 v[120:121], v[8:9]
	v_mov_b64_e32 v[118:119], v[6:7]
	v_mov_b64_e32 v[116:117], v[4:5]
	v_mov_b64_e32 v[114:115], v[2:3]
	v_mov_b64_e32 v[112:113], v[0:1]
	s_mov_b32 s58, 0
	v_mov_b64_e32 v[150:151], v[144:145]
	s_waitcnt lgkmcnt(0)
	s_barrier

.LBB0_40:
	s_add_i32 s60, s59, 0
	v_add_u32_e32 v144, s60, v196
	ds_read_b128 v[188:191], v144
	ds_read_b128 v[200:203], v197
	v_xad_u32 v144, v196, 32, s60
	ds_read_b128 v[204:207], v144
	v_xor_b32_e32 v199, 32, v197
	ds_read_b128 v[216:219], v199
	v_xad_u32 v144, v196, 64, s60
	ds_read_b128 v[220:223], v144
	v_xor_b32_e32 v199, 64, v197
	ds_read_b128 v[224:227], v199
	s_waitcnt lgkmcnt(4)
	v_mfma_f32_32x32x16_bf16 v[128:143], v[188:191], v[200:203], 0
	v_xor_b32_e32 v144, 0x60, v196
	v_add_u32_e32 v144, s60, v144
	ds_read_b128 v[188:191], v144
	v_xor_b32_e32 v199, 0x60, v197
	ds_read_b128 v[200:203], v199
	s_waitcnt lgkmcnt(4)
	v_mfma_f32_32x32x16_bf16 v[128:143], v[204:207], v[216:219], v[128:143]
	v_xor_b32_e32 v144, 0x80, v196
	v_add_u32_e32 v144, s60, v144
	ds_read_b128 v[204:207], v144
	v_xor_b32_e32 v199, 0x80, v197
	ds_read_b128 v[216:219], v199
	s_waitcnt lgkmcnt(4)
	v_mfma_f32_32x32x16_bf16 v[128:143], v[220:223], v[224:227], v[128:143]
	v_xor_b32_e32 v144, 0xa0, v196
	v_add_u32_e32 v144, s60, v144
	ds_read_b128 v[220:223], v144
	v_xor_b32_e32 v199, 0xa0, v197
	ds_read_b128 v[224:227], v199
	s_waitcnt lgkmcnt(4)
	v_mfma_f32_32x32x16_bf16 v[128:143], v[188:191], v[200:203], v[128:143]
	v_xor_b32_e32 v144, 0xc0, v196
	v_add_u32_e32 v144, s60, v144
	ds_read_b128 v[188:191], v144
	v_xor_b32_e32 v199, 0xc0, v197
	ds_read_b128 v[200:203], v199
	s_waitcnt lgkmcnt(4)
	v_mfma_f32_32x32x16_bf16 v[156:171], v[204:207], v[216:219], 0
	v_xor_b32_e32 v144, 0xe0, v196
	v_add_u32_e32 v144, s60, v144
	ds_read_b128 v[204:207], v144
	v_xor_b32_e32 v199, 0xe0, v197
	ds_read_b128 v[216:219], v199
	s_waitcnt lgkmcnt(4)
	v_mfma_f32_32x32x16_bf16 v[156:171], v[220:223], v[224:227], v[156:171]
	v_add_u32_e32 v144, s60, v196
	ds_read_b128 v[220:223], v144 offset:8192
	ds_read_b128 v[224:227], v197
	v_exp_f32_e32 v128, v128
	v_exp_f32_e32 v129, v129
	v_exp_f32_e32 v130, v130
	v_exp_f32_e32 v131, v131
	v_exp_f32_e32 v132, v132
	s_waitcnt lgkmcnt(4)
	v_mfma_f32_32x32x16_bf16 v[156:171], v[188:191], v[200:203], v[156:171]
	v_xad_u32 v144, v196, 32, s60
	ds_read_b128 v[188:191], v144 offset:8192
	v_xor_b32_e32 v199, 32, v197
	ds_read_b128 v[200:203], v199
	v_exp_f32_e32 v133, v133
	v_exp_f32_e32 v134, v134
	v_exp_f32_e32 v135, v135
	v_exp_f32_e32 v136, v136
	v_exp_f32_e32 v137, v137
	s_waitcnt lgkmcnt(4)
	v_mfma_f32_32x32x16_bf16 v[156:171], v[204:207], v[216:219], v[156:171]
	v_xad_u32 v144, v196, 64, s60
	ds_read_b128 v[204:207], v144 offset:8192
	v_xor_b32_e32 v199, 64, v197
	ds_read_b128 v[216:219], v199
	v_exp_f32_e32 v138, v138
	v_exp_f32_e32 v139, v139
	v_exp_f32_e32 v140, v140
	v_exp_f32_e32 v141, v141
	v_exp_f32_e32 v142, v142
	s_waitcnt lgkmcnt(4)
	v_mfma_f32_32x32x16_bf16 v[172:187], v[220:223], v[224:227], 0
	v_xor_b32_e32 v144, 0x60, v196
	v_add_u32_e32 v144, s60, v144
	ds_read_b128 v[220:223], v144 offset:8192
	v_xor_b32_e32 v199, 0x60, v197
	ds_read_b128 v[224:227], v199
	v_exp_f32_e32 v143, v143
	v_add_f32_e32 v192, v128, v129
	v_add_f32_e32 v193, v130, v131
	v_add_f32_e32 v192, v192, v132
	v_add_f32_e32 v193, v193, v133
	v_add_f32_e32 v192, v192, v134
	v_add_f32_e32 v193, v193, v135
	v_add_f32_e32 v192, v192, v136
	v_add_f32_e32 v193, v193, v137
	v_add_f32_e32 v192, v192, v138
	s_waitcnt lgkmcnt(4)
	v_mfma_f32_32x32x16_bf16 v[172:187], v[188:191], v[200:203], v[172:187]
	v_xor_b32_e32 v144, 0x80, v196
	v_add_u32_e32 v144, s60, v144
	ds_read_b128 v[188:191], v144 offset:8192
	v_xor_b32_e32 v199, 0x80, v197
	ds_read_b128 v[200:203], v199
	v_add_f32_e32 v193, v193, v139
	v_add_f32_e32 v192, v192, v140
	v_add_f32_e32 v193, v193, v141
	v_add_f32_e32 v192, v192, v142
	v_add_f32_e32 v193, v193, v143
	v_add_f32_e32 v192, v192, v193
	v_add_f32_e32 v150, v150, v192
	v_cvt_pk_bf16_f32 v128, v128, v129
	v_cvt_pk_bf16_f32 v129, v130, v131
	v_cvt_pk_bf16_f32 v130, v132, v133
	v_cvt_pk_bf16_f32 v131, v134, v135
	s_waitcnt lgkmcnt(4)
	v_mfma_f32_32x32x16_bf16 v[172:187], v[204:207], v[216:219], v[172:187]
	v_xor_b32_e32 v144, 0xa0, v196
	v_add_u32_e32 v144, s60, v144
	ds_read_b128 v[204:207], v144 offset:8192
	v_xor_b32_e32 v199, 0xa0, v197
	ds_read_b128 v[216:219], v199
	v_cvt_pk_bf16_f32 v132, v136, v137
	v_cvt_pk_bf16_f32 v133, v138, v139
	v_cvt_pk_bf16_f32 v134, v140, v141
	v_cvt_pk_bf16_f32 v135, v142, v143
	v_exp_f32_e32 v156, v156
	v_exp_f32_e32 v157, v157
	v_exp_f32_e32 v158, v158
	s_waitcnt lgkmcnt(4)
	v_mfma_f32_32x32x16_bf16 v[172:187], v[220:223], v[224:227], v[172:187]
	v_xor_b32_e32 v144, 0xc0, v196
	v_add_u32_e32 v144, s60, v144
	ds_read_b128 v[220:223], v144 offset:8192
	v_xor_b32_e32 v199, 0xc0, v197
	ds_read_b128 v[224:227], v199
	v_exp_f32_e32 v159, v159
	v_exp_f32_e32 v160, v160
	v_exp_f32_e32 v161, v161
	v_exp_f32_e32 v162, v162
	v_exp_f32_e32 v163, v163
	s_waitcnt lgkmcnt(4)
	v_mfma_f32_32x32x16_bf16 v[228:243], v[188:191], v[200:203], 0
	v_xor_b32_e32 v144, 0xe0, v196
	v_add_u32_e32 v144, s60, v144
	ds_read_b128 v[188:191], v144 offset:8192
	v_xor_b32_e32 v199, 0xe0, v197
	ds_read_b128 v[200:203], v199
	v_exp_f32_e32 v164, v164
	v_exp_f32_e32 v165, v165
	v_exp_f32_e32 v166, v166
	v_exp_f32_e32 v167, v167
	v_exp_f32_e32 v168, v168
	s_waitcnt lgkmcnt(4)
	v_mfma_f32_32x32x16_bf16 v[228:243], v[204:207], v[216:219], v[228:243]
	v_add_u32_e32 v248, s60, v198
	v_xad_u32 v249, v198, 32, s60
	ds_read_b128 v[204:207], v248
	ds_read_b128 v[216:219], v249
	v_exp_f32_e32 v169, v169
	v_exp_f32_e32 v170, v170
	v_exp_f32_e32 v171, v171
	v_add_f32_e32 v192, v156, v157
	v_add_f32_e32 v193, v158, v159
	v_add_f32_e32 v192, v192, v160
	v_add_f32_e32 v193, v193, v161
	v_add_f32_e32 v192, v192, v162
	s_waitcnt lgkmcnt(4)
	v_mfma_f32_32x32x16_bf16 v[228:243], v[220:223], v[224:227], v[228:243]
	ds_read_b128 v[220:223], v248 offset:4096
	ds_read_b128 v[224:227], v249 offset:4096
	v_add_f32_e32 v193, v193, v163
	v_add_f32_e32 v192, v192, v164
	v_add_f32_e32 v193, v193, v165
	v_add_f32_e32 v192, v192, v166
	v_add_f32_e32 v193, v193, v167
	v_add_f32_e32 v192, v192, v168
	v_add_f32_e32 v193, v193, v169
	v_add_f32_e32 v192, v192, v170
	v_add_f32_e32 v193, v193, v171
	v_add_f32_e32 v192, v192, v193
	v_add_f32_e32 v151, v151, v192
	s_waitcnt lgkmcnt(4)
	v_mfma_f32_32x32x16_bf16 v[228:243], v[188:191], v[200:203], v[228:243]
	ds_read_b128 v[188:191], v248 offset:8192
	ds_read_b128 v[200:203], v249 offset:8192
	v_cvt_pk_bf16_f32 v156, v156, v157
	v_cvt_pk_bf16_f32 v157, v158, v159
	v_cvt_pk_bf16_f32 v158, v160, v161
	v_cvt_pk_bf16_f32 v159, v162, v163
	v_cvt_pk_bf16_f32 v160, v164, v165
	v_cvt_pk_bf16_f32 v161, v166, v167
	v_cvt_pk_bf16_f32 v162, v168, v169
	v_cvt_pk_bf16_f32 v163, v170, v171
	v_exp_f32_e32 v172, v172
	s_waitcnt lgkmcnt(4)
	v_mfma_f32_32x32x16_bf16 v[112:127], v[204:207], v[128:131], v[112:127]
	v_exp_f32_e32 v173, v173
	v_exp_f32_e32 v174, v174
	v_exp_f32_e32 v175, v175
	v_exp_f32_e32 v176, v176
	v_mfma_f32_32x32x16_bf16 v[96:111], v[204:207], v[156:159], v[96:111]
	v_exp_f32_e32 v177, v177
	v_exp_f32_e32 v178, v178
	v_exp_f32_e32 v179, v179
	v_exp_f32_e32 v180, v180
	v_mfma_f32_32x32x16_bf16 v[112:127], v[216:219], v[132:135], v[112:127]
	v_exp_f32_e32 v181, v181
	v_exp_f32_e32 v182, v182
	v_exp_f32_e32 v183, v183
	v_exp_f32_e32 v184, v184
	v_mfma_f32_32x32x16_bf16 v[96:111], v[216:219], v[160:163], v[96:111]
	ds_read_b128 v[204:207], v248 offset:12288
	ds_read_b128 v[216:219], v249 offset:12288
	v_exp_f32_e32 v185, v185
	v_exp_f32_e32 v186, v186
	v_exp_f32_e32 v187, v187
	v_add_f32_e32 v192, v172, v173
	v_add_f32_e32 v193, v174, v175
	v_add_f32_e32 v192, v192, v176
	s_waitcnt lgkmcnt(4)
	v_mfma_f32_32x32x16_bf16 v[80:95], v[220:223], v[128:131], v[80:95]
	v_add_f32_e32 v193, v193, v177
	v_add_f32_e32 v192, v192, v178
	v_add_f32_e32 v193, v193, v179
	v_add_f32_e32 v192, v192, v180
	v_add_f32_e32 v193, v193, v181
	v_add_f32_e32 v192, v192, v182
	v_add_f32_e32 v193, v193, v183
	v_add_f32_e32 v192, v192, v184
	v_add_f32_e32 v193, v193, v185
	v_mfma_f32_32x32x16_bf16 v[64:79], v[220:223], v[156:159], v[64:79]
	v_add_f32_e32 v192, v192, v186
	v_add_f32_e32 v193, v193, v187
	v_add_f32_e32 v192, v192, v193
	v_add_f32_e32 v150, v150, v192
	v_cvt_pk_bf16_f32 v172, v172, v173
	v_cvt_pk_bf16_f32 v173, v174, v175
	v_cvt_pk_bf16_f32 v174, v176, v177
	v_cvt_pk_bf16_f32 v175, v178, v179
	v_cvt_pk_bf16_f32 v176, v180, v181
	v_mfma_f32_32x32x16_bf16 v[80:95], v[224:227], v[132:135], v[80:95]
	v_cvt_pk_bf16_f32 v177, v182, v183
	v_cvt_pk_bf16_f32 v178, v184, v185
	v_cvt_pk_bf16_f32 v179, v186, v187
	v_exp_f32_e32 v228, v228
	v_exp_f32_e32 v229, v229
	v_exp_f32_e32 v230, v230
	v_mfma_f32_32x32x16_bf16 v[64:79], v[224:227], v[160:163], v[64:79]
	v_xad_u32 v248, v198, 64, s60
	v_xor_b32_e32 v249, 0x60, v198
	v_add_u32_e32 v249, s60, v249
	ds_read_b128 v[220:223], v248
	ds_read_b128 v[224:227], v249
	v_exp_f32_e32 v231, v231
	v_exp_f32_e32 v232, v232
	v_exp_f32_e32 v233, v233
	v_exp_f32_e32 v234, v234
	s_waitcnt lgkmcnt(4)
	v_mfma_f32_32x32x16_bf16 v[48:63], v[188:191], v[128:131], v[48:63]
	v_exp_f32_e32 v235, v235
	v_exp_f32_e32 v236, v236
	v_exp_f32_e32 v237, v237
	v_exp_f32_e32 v238, v238
	v_mfma_f32_32x32x16_bf16 v[32:47], v[188:191], v[156:159], v[32:47]
	v_exp_f32_e32 v239, v239
	v_exp_f32_e32 v240, v240
	v_exp_f32_e32 v241, v241
	v_exp_f32_e32 v242, v242
	v_mfma_f32_32x32x16_bf16 v[48:63], v[200:203], v[132:135], v[48:63]
	v_exp_f32_e32 v243, v243
	v_add_f32_e32 v192, v228, v229
	v_add_f32_e32 v193, v230, v231
	v_add_f32_e32 v192, v192, v232
	v_add_f32_e32 v193, v193, v233
	v_add_f32_e32 v192, v192, v234
	v_add_f32_e32 v193, v193, v235
	v_add_f32_e32 v192, v192, v236
	v_mfma_f32_32x32x16_bf16 v[32:47], v[200:203], v[160:163], v[32:47]
	ds_read_b128 v[188:191], v248 offset:4096
	ds_read_b128 v[200:203], v249 offset:4096
	v_add_f32_e32 v193, v193, v237
	v_add_f32_e32 v192, v192, v238
	v_add_f32_e32 v193, v193, v239
	v_add_f32_e32 v192, v192, v240
	v_add_f32_e32 v193, v193, v241
	v_add_f32_e32 v192, v192, v242
	v_add_f32_e32 v193, v193, v243
	v_add_f32_e32 v192, v192, v193
	v_add_f32_e32 v151, v151, v192
	s_waitcnt lgkmcnt(4)
	v_mfma_f32_32x32x16_bf16 v[16:31], v[204:207], v[128:131], v[16:31]
	v_cvt_pk_bf16_f32 v228, v228, v229
	v_cvt_pk_bf16_f32 v229, v230, v231
	v_cvt_pk_bf16_f32 v230, v232, v233
	v_cvt_pk_bf16_f32 v231, v234, v235
	v_cvt_pk_bf16_f32 v232, v236, v237
	v_cvt_pk_bf16_f32 v233, v238, v239
	v_cvt_pk_bf16_f32 v234, v240, v241
	v_cvt_pk_bf16_f32 v235, v242, v243
	v_mfma_f32_32x32x16_bf16 v[0:15], v[204:207], v[156:159], v[0:15]
	v_mfma_f32_32x32x16_bf16 v[16:31], v[216:219], v[132:135], v[16:31]
	v_mfma_f32_32x32x16_bf16 v[0:15], v[216:219], v[160:163], v[0:15]
	ds_read_b128 v[204:207], v248 offset:8192
	ds_read_b128 v[216:219], v249 offset:8192
	s_waitcnt lgkmcnt(4)
	v_mfma_f32_32x32x16_bf16 v[112:127], v[220:223], v[172:175], v[112:127]
	v_mfma_f32_32x32x16_bf16 v[96:111], v[220:223], v[228:231], v[96:111]
	v_mfma_f32_32x32x16_bf16 v[112:127], v[224:227], v[176:179], v[112:127]
	v_mfma_f32_32x32x16_bf16 v[96:111], v[224:227], v[232:235], v[96:111]
	ds_read_b128 v[220:223], v248 offset:12288
	ds_read_b128 v[224:227], v249 offset:12288
	s_waitcnt lgkmcnt(4)
	v_mfma_f32_32x32x16_bf16 v[80:95], v[188:191], v[172:175], v[80:95]
	v_mfma_f32_32x32x16_bf16 v[64:79], v[188:191], v[228:231], v[64:79]
	v_mfma_f32_32x32x16_bf16 v[80:95], v[200:203], v[176:179], v[80:95]
	v_mfma_f32_32x32x16_bf16 v[64:79], v[200:203], v[232:235], v[64:79]
	s_waitcnt lgkmcnt(2)
	v_mfma_f32_32x32x16_bf16 v[48:63], v[204:207], v[172:175], v[48:63]
	v_mfma_f32_32x32x16_bf16 v[32:47], v[204:207], v[228:231], v[32:47]
	v_mfma_f32_32x32x16_bf16 v[48:63], v[216:219], v[176:179], v[48:63]
	v_mfma_f32_32x32x16_bf16 v[32:47], v[216:219], v[232:235], v[32:47]
	s_waitcnt lgkmcnt(0)
	v_mfma_f32_32x32x16_bf16 v[16:31], v[220:223], v[172:175], v[16:31]
	v_mfma_f32_32x32x16_bf16 v[0:15], v[220:223], v[228:231], v[0:15]
	v_mfma_f32_32x32x16_bf16 v[16:31], v[224:227], v[176:179], v[16:31]
	v_mfma_f32_32x32x16_bf16 v[0:15], v[224:227], v[232:235], v[0:15]
	s_mov_b64 s[92:93], -1
	s_and_b64 vcc, exec, s[86:87]
	s_cbranch_vccnz .LBB0_38

.LBB0_43:
	s_add_i32 s60, s59, 0x8000
	s_cmp_lg_u32 s59, 0x10000
	s_cselect_b32 s60, s60, 0
	s_add_i32 s58, s58, 1
	v_lshl_add_u64 v[146:147], v[146:147], 0, s[14:15]
	v_lshl_add_u64 v[148:149], v[148:149], 0, s[14:15]
	v_lshl_add_u64 v[152:153], v[152:153], 0, s[18:19]
	s_cmp_eq_u32 s56, s58
	v_lshl_add_u64 v[154:155], v[154:155], 0, s[18:19]
	s_waitcnt lgkmcnt(0)
	s_barrier
	s_cbranch_scc1 .LBB0_33
	s_mov_b32 s61, s59
	s_branch .LBB0_35

.LBB0_48:
	v_mov_b64_e32 v[174:175], 0
	v_mov_b64_e32 v[178:179], 0xb00
	v_mov_b64_e32 v[180:181], 0x200
	v_mov_b64_e32 v[182:183], 0x1ff
	v_mov_b64_e32 v[184:185], 0x2ff
	v_mov_b64_e32 v[186:187], 0x300
	s_barrier
	s_mov_b64 s[38:39], exec
	v_readlane_b32 s0, v252, 13
	v_readlane_b32 s1, v252, 14
	s_and_b64 s[0:1], s[38:39], s[0:1]
	s_mov_b64 exec, s[0:1]
	s_cbranch_execz .LBB0_50
	v_readlane_b32 s0, v254, 19
	s_nop 1
	v_mov_b32_e32 v0, s0
	v_readlane_b32 s0, v254, 57
	s_nop 1
	v_mov_b32_e32 v1, s0
	v_readlane_b32 s0, v254, 20
	ds_write_b32 v0, v1
	s_nop 0
	v_mov_b32_e32 v0, s0
	v_readlane_b32 s0, v255, 0
	s_nop 1
	v_mov_b32_e32 v1, s0
	v_readlane_b32 s0, v254, 18
	ds_write_b32 v0, v1
	s_nop 0
	v_mov_b32_e32 v0, s0
	v_readlane_b32 s0, v255, 1
	s_nop 1
	v_mov_b32_e32 v1, s0
	v_readlane_b32 s0, v254, 17
	ds_write_b32 v0, v1
	s_nop 0
	v_mov_b32_e32 v0, s0
	v_readlane_b32 s0, v255, 2
	s_nop 1
	v_mov_b32_e32 v1, s0
	ds_write_b32 v0, v1
